# plus phase 2 k-norm: all 36 row loads issued up front with recounted waits
# baseline (speedup 1.0000x reference)
; DI void ph_knorm(const Params& p) {
;     ...
;     for (int u = gw; u < BATCH * 456; u += nw) {
;         const int b = u / 456, ch = u - b * 456;
;         float mxa = 0.f, mxb = 0.f;
;         const bf16_t* base = PQK + ((size_t)b * LT + ch * 18) * 2048 + lane * 8;
; #pragma unroll
;         for (int i = 0; i < 18; ++i) {
;             const u32x4 va = *(const u32x4*)(base + (size_t)i * 2048 + 512), vb = *(const u32x4*)(base + (size_t)i * 2048 + 1536);
;             float sa = 0.f, sb = 0.f;
; #pragma unroll
;             for (int e = 0; e < 4; ++e) {
;                 const float a0 = __uint_as_float(va[e] << 16), a1 = __uint_as_float(va[e] & 0xffff0000u);
;                 const float b0 = __uint_as_float(vb[e] << 16), b1 = __uint_as_float(vb[e] & 0xffff0000u);
;                 sa += a0 * a0 + a1 * a1; sb += b0 * b0 + b1 * b1;
;             }
;             sa += __shfl_xor(sa, 1); sa += __shfl_xor(sa, 2); sa += __shfl_xor(sa, 4);
;             sb += __shfl_xor(sb, 1); sb += __shfl_xor(sb, 2); sb += __shfl_xor(sb, 4);
;             mxa = fmaxf(mxa, sa); mxb = fmaxf(mxb, sb);
;         }
.LBB0_538:
	v_mul_hi_i32 v0, v14, s8
	v_add_u32_e32 v0, v0, v14
	v_lshrrev_b32_e32 v1, 31, v0
	v_ashrrev_i32_e32 v0, 8, v0
	v_add_u32_e32 v18, v0, v1
	v_mad_i32_i24 v2, v18, s9, v14
	v_mul_lo_u32 v2, v2, 18
	v_mul_hi_i32_i24_e32 v1, 0x2010, v18
	v_mul_i32_i24_e32 v0, 0x2010, v18
	v_ashrrev_i32_e32 v3, 31, v2
	v_lshl_add_u64 v[0:1], v[0:1], 0, v[2:3]
	v_lshlrev_b64 v[0:1], 12, v[0:1]
	s_waitcnt lgkmcnt(5)
	v_lshl_add_u64 v[12:13], v[8:9], 0, v[0:1]
	s_nop 0
	v_readfirstlane_b32 s88, v12
	v_readfirstlane_b32 s89, v13
	v_and_b32_e32 v244, 63, v210
	v_lshlrev_b32_e32 v244, 4, v244
	s_nop 4
	global_load_dwordx4 v[96:99], v244, s[88:89] offset:1024
	global_load_dwordx4 v[100:103], v244, s[88:89] offset:3072
	s_add_u32 s94, s88, 0x1000
	s_addc_u32 s95, s89, 0
	s_nop 0
	global_load_dwordx4 v[104:107], v244, s[94:95] offset:1024
	global_load_dwordx4 v[108:111], v244, s[94:95] offset:3072
	s_add_u32 s92, s88, 0x2000
	s_addc_u32 s93, s89, 0
	s_nop 0
	global_load_dwordx4 v[112:115], v244, s[92:93] offset:1024
	global_load_dwordx4 v[116:119], v244, s[92:93] offset:3072
	s_add_u32 s94, s88, 0x3000
	s_addc_u32 s95, s89, 0
	s_nop 0
	global_load_dwordx4 v[120:123], v244, s[94:95] offset:1024
	global_load_dwordx4 v[124:127], v244, s[94:95] offset:3072
	s_add_u32 s92, s88, 0x4000
	s_addc_u32 s93, s89, 0
	s_nop 0
	global_load_dwordx4 v[128:131], v244, s[92:93] offset:1024
	global_load_dwordx4 v[132:135], v244, s[92:93] offset:3072
	s_add_u32 s94, s88, 0x5000
	s_addc_u32 s95, s89, 0
	s_nop 0
	global_load_dwordx4 v[136:139], v244, s[94:95] offset:1024
	global_load_dwordx4 v[140:143], v244, s[94:95] offset:3072
	s_add_u32 s92, s88, 0x6000
	s_addc_u32 s93, s89, 0
	s_nop 0
	global_load_dwordx4 v[144:147], v244, s[92:93] offset:1024
	global_load_dwordx4 v[148:151], v244, s[92:93] offset:3072
	s_add_u32 s94, s88, 0x7000
	s_addc_u32 s95, s89, 0
	s_nop 0
	global_load_dwordx4 v[152:155], v244, s[94:95] offset:1024
	global_load_dwordx4 v[156:159], v244, s[94:95] offset:3072
	s_add_u32 s92, s88, 0x8000
	s_addc_u32 s93, s89, 0
	s_nop 0
	global_load_dwordx4 v[160:163], v244, s[92:93] offset:1024
	global_load_dwordx4 v[164:167], v244, s[92:93] offset:3072
	s_add_u32 s94, s88, 0x9000
	s_addc_u32 s95, s89, 0
	s_nop 0
	global_load_dwordx4 v[168:171], v244, s[94:95] offset:1024
	global_load_dwordx4 v[172:175], v244, s[94:95] offset:3072
	s_add_u32 s92, s88, 0xa000
	s_addc_u32 s93, s89, 0
	s_nop 0
	global_load_dwordx4 v[176:179], v244, s[92:93] offset:1024
	global_load_dwordx4 v[180:183], v244, s[92:93] offset:3072
	s_add_u32 s94, s88, 0xb000
	s_addc_u32 s95, s89, 0
	s_nop 0
	global_load_dwordx4 v[184:187], v244, s[94:95] offset:1024
	global_load_dwordx4 v[188:191], v244, s[94:95] offset:3072
	s_add_u32 s92, s88, 0xc000
	s_addc_u32 s93, s89, 0
	s_nop 0
	global_load_dwordx4 v[192:195], v244, s[92:93] offset:1024
	global_load_dwordx4 v[196:199], v244, s[92:93] offset:3072
	s_add_u32 s94, s88, 0xd000
	s_addc_u32 s95, s89, 0
	s_nop 0
	global_load_dwordx4 v[200:203], v244, s[94:95] offset:1024
	global_load_dwordx4 v[204:207], v244, s[94:95] offset:3072
	s_add_u32 s92, s88, 0xe000
	s_addc_u32 s93, s89, 0
	s_nop 0
	global_load_dwordx4 v[212:215], v244, s[92:93] offset:1024
	global_load_dwordx4 v[216:219], v244, s[92:93] offset:3072
	s_add_u32 s94, s88, 0xf000
	s_addc_u32 s95, s89, 0
	s_nop 0
	global_load_dwordx4 v[220:223], v244, s[94:95] offset:1024
	global_load_dwordx4 v[224:227], v244, s[94:95] offset:3072
	s_add_u32 s92, s88, 0x10000
	s_addc_u32 s93, s89, 0
	s_nop 0
	global_load_dwordx4 v[228:231], v244, s[92:93] offset:1024
	global_load_dwordx4 v[232:235], v244, s[92:93] offset:3072
	s_add_u32 s94, s88, 0x11000
	s_addc_u32 s95, s89, 0
	s_nop 0
	global_load_dwordx4 v[236:239], v244, s[94:95] offset:1024
	global_load_dwordx4 v[240:243], v244, s[94:95] offset:3072
	v_add_co_u32_e64 v0, s[0:1], s10, v12
	s_waitcnt vmcnt(35)
	v_lshlrev_b32_e32 v19, 16, v96
	v_addc_co_u32_e64 v1, s[0:1], 0, v13, s[0:1]
	v_add_co_u32_e64 v0, s[0:1], s11, v12
	v_and_b32_e32 v20, 0xffff0000, v96
	s_nop 0
	v_addc_co_u32_e64 v1, s[0:1], 0, v13, s[0:1]
	v_add_co_u32_e64 v2, s[0:1], s12, v12
	v_lshlrev_b32_e32 v45, 16, v97
	s_nop 0
	v_addc_co_u32_e64 v3, s[0:1], 0, v13, s[0:1]
	s_nop 0
	v_and_b32_e32 v21, 0xffff0000, v97
	v_lshlrev_b32_e32 v47, 16, v98
	v_and_b32_e32 v22, 0xffff0000, v98
	v_mul_f32_e32 v20, v20, v20
	v_mul_f32_e32 v21, v21, v21
	v_lshlrev_b32_e32 v49, 16, v99
	v_and_b32_e32 v23, 0xffff0000, v99
	v_mul_f32_e32 v22, v22, v22
	v_fmac_f32_e32 v20, v19, v19
	v_fmac_f32_e32 v21, v45, v45
	v_mul_f32_e32 v23, v23, v23
	v_fmac_f32_e32 v22, v47, v47
	v_add_f32_e32 v20, v20, v21
	v_fmac_f32_e32 v23, v49, v49
	v_add_f32_e32 v20, v22, v20
	v_add_f32_e32 v20, v23, v20
	ds_bpermute_b32 v22, v15, v20
	s_waitcnt vmcnt(34)
	v_lshlrev_b32_e32 v44, 16, v100
	v_and_b32_e32 v24, 0xffff0000, v100
	v_lshlrev_b32_e32 v46, 16, v101
	v_and_b32_e32 v25, 0xffff0000, v101
	s_waitcnt lgkmcnt(0)
	v_add_f32_e32 v20, v20, v22
	ds_bpermute_b32 v22, v16, v20
	v_mul_f32_e32 v24, v24, v24
	v_mul_f32_e32 v25, v25, v25
	v_fmac_f32_e32 v24, v44, v44
	v_fmac_f32_e32 v25, v46, v46
	v_lshlrev_b32_e32 v48, 16, v102
	v_and_b32_e32 v26, 0xffff0000, v102
	v_add_f32_e32 v21, v24, v25
	v_lshlrev_b32_e32 v50, 16, v103
	v_and_b32_e32 v27, 0xffff0000, v103
	v_mul_f32_e32 v26, v26, v26
	v_mul_f32_e32 v27, v27, v27
	v_fmac_f32_e32 v26, v48, v48
	v_fmac_f32_e32 v27, v50, v50
	v_add_f32_e32 v21, v26, v21
	v_add_f32_e32 v21, v27, v21
	ds_bpermute_b32 v25, v15, v21
	s_waitcnt lgkmcnt(0)
	v_add_f32_e32 v21, v21, v25
	ds_bpermute_b32 v25, v16, v21
	s_waitcnt vmcnt(33)
; DI void ph_knorm(const Params& p) {
;     ...
;         const bf16_t* base = PQK + ((size_t)b * LT + ch * 18) * 2048 + lane * 8;
; #pragma unroll
;         for (int i = 0; i < 18; ++i) {
;             const u32x4 va = *(const u32x4*)(base + (size_t)i * 2048 + 512), vb = *(const u32x4*)(base + (size_t)i * 2048 + 1536);
;             float sa = 0.f, sb = 0.f;
; #pragma unroll
;             for (int e = 0; e < 4; ++e) {
;                 const float a0 = __uint_as_float(va[e] << 16), a1 = __uint_as_float(va[e] & 0xffff0000u);
;                 const float b0 = __uint_as_float(vb[e] << 16), b1 = __uint_as_float(vb[e] & 0xffff0000u);
;                 sa += a0 * a0 + a1 * a1; sb += b0 * b0 + b1 * b1;
;             }
;             sa += __shfl_xor(sa, 1); sa += __shfl_xor(sa, 2); sa += __shfl_xor(sa, 4);
;             sb += __shfl_xor(sb, 1); sb += __shfl_xor(sb, 2); sb += __shfl_xor(sb, 4);
;             mxa = fmaxf(mxa, sa); mxb = fmaxf(mxb, sb);
;         }
	v_lshlrev_b32_e32 v51, 16, v104
	v_and_b32_e32 v28, 0xffff0000, v104
	v_lshlrev_b32_e32 v53, 16, v105
	v_and_b32_e32 v29, 0xffff0000, v105
	v_lshlrev_b32_e32 v55, 16, v106
	v_and_b32_e32 v30, 0xffff0000, v106
	v_mul_f32_e32 v19, v28, v28
	v_mul_f32_e32 v29, v29, v29
	v_mul_f32_e32 v30, v30, v30
	v_fmac_f32_e32 v19, v51, v51
	v_fmac_f32_e32 v29, v53, v53
	s_waitcnt vmcnt(32)
	v_lshlrev_b32_e32 v52, 16, v108
	v_and_b32_e32 v32, 0xffff0000, v108
	v_lshlrev_b32_e32 v54, 16, v109
	v_and_b32_e32 v33, 0xffff0000, v109
	v_lshlrev_b32_e32 v57, 16, v107
	v_and_b32_e32 v31, 0xffff0000, v107
	v_fmac_f32_e32 v30, v55, v55
	v_add_f32_e32 v19, v19, v29
	v_lshlrev_b32_e32 v56, 16, v110
	v_and_b32_e32 v34, 0xffff0000, v110
	v_mul_f32_e32 v28, v32, v32
	v_mul_f32_e32 v32, v33, v33
	v_add_f32_e32 v24, v30, v19
	v_add_f32_e32 v19, v20, v22
	v_mul_f32_e32 v22, v31, v31
	v_lshlrev_b32_e32 v58, 16, v111
	v_and_b32_e32 v35, 0xffff0000, v111
	v_mul_f32_e32 v33, v34, v34
	v_fmac_f32_e32 v28, v52, v52
	v_fmac_f32_e32 v32, v54, v54
	v_fmac_f32_e32 v22, v57, v57
	v_fmac_f32_e32 v33, v56, v56
	v_add_f32_e32 v23, v28, v32
	v_add_f32_e32 v22, v22, v24
	v_mul_f32_e32 v24, v35, v35
	v_add_f32_e32 v23, v33, v23
	v_fmac_f32_e32 v24, v58, v58
	v_add_f32_e32 v23, v24, v23
	ds_bpermute_b32 v24, v15, v23
	s_waitcnt vmcnt(30)
	v_and_b32_e32 v30, 0xffff0000, v116
	v_lshlrev_b32_e32 v29, 16, v116
	v_and_b32_e32 v32, 0xffff0000, v117
	v_lshlrev_b32_e32 v31, 16, v117
	s_waitcnt lgkmcnt(0)
	v_add_f32_e32 v27, v23, v24
	ds_bpermute_b32 v28, v16, v27
	v_add_f32_e32 v23, v21, v25
	v_and_b32_e32 v40, 0xffff0000, v118
	ds_bpermute_b32 v26, v15, v22
	ds_bpermute_b32 v20, v17, v19
	s_waitcnt lgkmcnt(2)
	v_add_f32_e32 v25, v27, v28
	v_and_b32_e32 v28, 0xffff0000, v112
	v_lshlrev_b32_e32 v27, 16, v112
	v_mul_f32_e32 v28, v28, v28
	v_fmac_f32_e32 v28, v27, v27
	v_mul_f32_e32 v27, v30, v30
	v_and_b32_e32 v30, 0xffff0000, v113
	v_fmac_f32_e32 v27, v29, v29
	v_lshlrev_b32_e32 v29, 16, v113
	v_mul_f32_e32 v30, v30, v30
	v_fmac_f32_e32 v30, v29, v29
	v_add_f32_e32 v34, v28, v30
	v_mul_f32_e32 v28, v32, v32
	v_fmac_f32_e32 v28, v31, v31
	v_and_b32_e32 v29, 0xffff0000, v114
	v_add_f32_e32 v27, v27, v28
	v_lshlrev_b32_e32 v28, 16, v114
	v_mul_f32_e32 v35, v29, v29
	v_fmac_f32_e32 v35, v28, v28
	v_add_co_u32_e64 v28, s[0:1], s13, v12
	v_add_f32_e32 v41, v35, v34
	s_nop 0
	v_addc_co_u32_e64 v29, s[0:1], 0, v13, s[0:1]
	v_lshlrev_b32_e32 v38, 16, v118
	v_lshlrev_b32_e32 v28, 16, v115
	v_and_b32_e32 v29, 0xffff0000, v115
	v_mul_f32_e32 v39, v40, v40
	v_fmac_f32_e32 v39, v38, v38
	v_add_f32_e32 v27, v39, v27
	v_and_b32_e32 v39, 0xffff0000, v119
	v_lshlrev_b32_e32 v38, 16, v119
	v_mul_f32_e32 v39, v39, v39
	v_fmac_f32_e32 v39, v38, v38
	v_add_f32_e32 v46, v39, v27
	s_waitcnt vmcnt(29)
	v_lshlrev_b32_e32 v38, 16, v120
	v_and_b32_e32 v4, 0xffff0000, v120
	s_waitcnt vmcnt(28)
	v_lshlrev_b32_e32 v39, 16, v124
	v_and_b32_e32 v0, 0xffff0000, v124
	v_mul_f32_e32 v4, v4, v4
	v_mul_f32_e32 v0, v0, v0
	v_fmac_f32_e32 v4, v38, v38
	v_fmac_f32_e32 v0, v39, v39
	v_lshlrev_b32_e32 v38, 16, v121
	v_and_b32_e32 v5, 0xffff0000, v121
	v_lshlrev_b32_e32 v39, 16, v125
	v_and_b32_e32 v1, 0xffff0000, v125
	v_mul_f32_e32 v5, v5, v5
	v_mul_f32_e32 v1, v1, v1
	v_fmac_f32_e32 v5, v38, v38
	v_fmac_f32_e32 v1, v39, v39
	v_add_f32_e32 v4, v4, v5
	v_add_f32_e32 v5, v0, v1
	v_and_b32_e32 v1, 0xffff0000, v122
	v_lshlrev_b32_e32 v0, 16, v122
	v_mul_f32_e32 v42, v1, v1
	v_mul_f32_e32 v29, v29, v29
	v_fmac_f32_e32 v42, v0, v0
	v_add_co_u32_e64 v0, s[0:1], s14, v12
	v_fmac_f32_e32 v29, v28, v28
	s_nop 0
	v_addc_co_u32_e64 v1, s[0:1], 0, v13, s[0:1]
	v_add_f32_e32 v28, v29, v41
	v_add_f32_e32 v4, v42, v4
	ds_bpermute_b32 v29, v15, v28
	v_lshlrev_b32_e32 v6, 16, v126
	v_and_b32_e32 v2, 0xffff0000, v126
	v_mul_f32_e32 v0, v2, v2
	v_and_b32_e32 v2, 0xffff0000, v123
	s_waitcnt lgkmcnt(0)
	v_add_f32_e32 v28, v28, v29
	ds_bpermute_b32 v29, v16, v28
	v_fmac_f32_e32 v0, v6, v6
	v_lshlrev_b32_e32 v1, 16, v123
	v_mul_f32_e32 v2, v2, v2
	v_add_f32_e32 v0, v0, v5
	v_lshlrev_b32_e32 v5, 16, v127
	v_and_b32_e32 v3, 0xffff0000, v127
	v_fmac_f32_e32 v2, v1, v1
	v_add_f32_e32 v1, v2, v4
	v_mul_f32_e32 v2, v3, v3
	v_fmac_f32_e32 v2, v5, v5
	v_add_f32_e32 v0, v2, v0
	s_waitcnt lgkmcnt(0)
	v_add_f32_e32 v27, v28, v29
	ds_bpermute_b32 v29, v15, v46
	ds_bpermute_b32 v2, v15, v0
	ds_bpermute_b32 v3, v15, v1
	v_add_f32_e32 v22, v22, v26
	ds_bpermute_b32 v26, v16, v22
	s_waitcnt lgkmcnt(3)
	v_add_f32_e32 v4, v46, v29
	s_waitcnt lgkmcnt(2)
	v_add_f32_e32 v7, v0, v2
	ds_bpermute_b32 v5, v16, v4
	s_waitcnt lgkmcnt(2)
	v_add_f32_e32 v1, v1, v3
	ds_bpermute_b32 v29, v16, v7
	ds_bpermute_b32 v6, v16, v1
	s_waitcnt lgkmcnt(3)
	v_add_f32_e32 v21, v22, v26
	s_waitcnt lgkmcnt(2)
	v_add_f32_e32 v2, v4, v5
	ds_bpermute_b32 v24, v17, v23
	s_waitcnt lgkmcnt(2)
	v_add_f32_e32 v4, v7, v29
	s_waitcnt lgkmcnt(1)
	v_add_f32_e32 v0, v1, v6
	s_waitcnt vmcnt(27)
	v_and_b32_e32 v7, 0xffff0000, v128
	v_lshlrev_b32_e32 v6, 16, v128
	s_waitcnt vmcnt(26)
	v_and_b32_e32 v30, 0xffff0000, v132
	v_mul_f32_e32 v7, v7, v7
	v_lshlrev_b32_e32 v29, 16, v132
	v_fmac_f32_e32 v7, v6, v6
	v_mul_f32_e32 v6, v30, v30
	v_and_b32_e32 v30, 0xffff0000, v129
	v_fmac_f32_e32 v6, v29, v29
	v_lshlrev_b32_e32 v29, 16, v129
	v_mul_f32_e32 v30, v30, v30
	v_and_b32_e32 v34, 0xffff0000, v133
	v_fmac_f32_e32 v30, v29, v29
	v_lshlrev_b32_e32 v31, 16, v133
	v_add_f32_e32 v29, v7, v30
	v_mul_f32_e32 v7, v34, v34
	v_fmac_f32_e32 v7, v31, v31
	v_add_f32_e32 v30, v6, v7
	v_and_b32_e32 v7, 0xffff0000, v130
	v_lshlrev_b32_e32 v6, 16, v130
	v_mul_f32_e32 v34, v7, v7
	v_fmac_f32_e32 v34, v6, v6
	v_add_co_u32_e64 v6, s[0:1], s15, v12
	v_and_b32_e32 v32, 0xffff0000, v134
	s_nop 0
	v_addc_co_u32_e64 v7, s[0:1], 0, v13, s[0:1]
	v_and_b32_e32 v7, 0xffff0000, v131
	v_lshlrev_b32_e32 v6, 16, v131
	v_mul_f32_e32 v7, v7, v7
	v_add_f32_e32 v29, v34, v29
	v_fmac_f32_e32 v7, v6, v6
	v_lshlrev_b32_e32 v31, 16, v134
	v_add_f32_e32 v6, v7, v29
	v_mul_f32_e32 v29, v32, v32
	v_fmac_f32_e32 v29, v31, v31
	v_and_b32_e32 v31, 0xffff0000, v135
	v_add_f32_e32 v29, v29, v30
	v_lshlrev_b32_e32 v30, 16, v135
	v_mul_f32_e32 v31, v31, v31
	v_fmac_f32_e32 v31, v30, v30
	v_add_f32_e32 v29, v31, v29
	s_waitcnt vmcnt(25)
; DI void ph_knorm(const Params& p) {
;     ...
;         for (int i = 0; i < 18; ++i) {
;             const u32x4 va = *(const u32x4*)(base + (size_t)i * 2048 + 512), vb = *(const u32x4*)(base + (size_t)i * 2048 + 1536);
;             float sa = 0.f, sb = 0.f;
; #pragma unroll
;             for (int e = 0; e < 4; ++e) {
;                 const float a0 = __uint_as_float(va[e] << 16), a1 = __uint_as_float(va[e] & 0xffff0000u);
;                 const float b0 = __uint_as_float(vb[e] << 16), b1 = __uint_as_float(vb[e] & 0xffff0000u);
;                 sa += a0 * a0 + a1 * a1; sb += b0 * b0 + b1 * b1;
;             }
;             sa += __shfl_xor(sa, 1); sa += __shfl_xor(sa, 2); sa += __shfl_xor(sa, 4);
;             sb += __shfl_xor(sb, 1); sb += __shfl_xor(sb, 2); sb += __shfl_xor(sb, 4);
;             mxa = fmaxf(mxa, sa); mxb = fmaxf(mxb, sb);
;         }
	v_and_b32_e32 v31, 0xffff0000, v136
	v_lshlrev_b32_e32 v30, 16, v136
	s_waitcnt vmcnt(24)
	v_and_b32_e32 v34, 0xffff0000, v140
	v_mul_f32_e32 v31, v31, v31
	v_lshlrev_b32_e32 v33, 16, v140
	v_fmac_f32_e32 v31, v30, v30
	v_mul_f32_e32 v30, v34, v34
	v_and_b32_e32 v34, 0xffff0000, v137
	v_fmac_f32_e32 v30, v33, v33
	v_lshlrev_b32_e32 v33, 16, v137
	v_mul_f32_e32 v34, v34, v34
	v_and_b32_e32 v36, 0xffff0000, v141
	v_fmac_f32_e32 v34, v33, v33
	v_lshlrev_b32_e32 v35, 16, v141
	v_add_f32_e32 v33, v31, v34
	v_mul_f32_e32 v31, v36, v36
	v_fmac_f32_e32 v31, v35, v35
	v_add_f32_e32 v34, v30, v31
	v_and_b32_e32 v31, 0xffff0000, v138
	v_lshlrev_b32_e32 v30, 16, v138
	v_mul_f32_e32 v37, v31, v31
	v_fmac_f32_e32 v37, v30, v30
	v_add_co_u32_e64 v30, s[0:1], s18, v12
	v_and_b32_e32 v36, 0xffff0000, v142
	s_nop 0
	v_addc_co_u32_e64 v31, s[0:1], 0, v13, s[0:1]
	v_lshlrev_b32_e32 v35, 16, v142
	v_mul_f32_e32 v30, v36, v36
	v_fmac_f32_e32 v30, v35, v35
	v_add_f32_e32 v30, v30, v34
	v_and_b32_e32 v34, 0xffff0000, v139
	v_lshlrev_b32_e32 v31, 16, v139
	v_mul_f32_e32 v34, v34, v34
	v_add_f32_e32 v33, v37, v33
	v_and_b32_e32 v36, 0xffff0000, v143
	v_fmac_f32_e32 v34, v31, v31
	v_lshlrev_b32_e32 v35, 16, v143
	v_add_f32_e32 v31, v34, v33
	v_mul_f32_e32 v33, v36, v36
	v_fmac_f32_e32 v33, v35, v35
	v_add_f32_e32 v30, v33, v30
	ds_bpermute_b32 v33, v15, v30
	ds_bpermute_b32 v32, v15, v29
	ds_bpermute_b32 v34, v15, v31
	ds_bpermute_b32 v7, v15, v6
	ds_bpermute_b32 v22, v17, v21
	s_waitcnt lgkmcnt(4)
	v_add_f32_e32 v33, v30, v33
	s_waitcnt lgkmcnt(3)
	v_add_f32_e32 v29, v29, v32
	s_waitcnt lgkmcnt(2)
	v_add_f32_e32 v34, v31, v34
	ds_bpermute_b32 v36, v16, v33
	ds_bpermute_b32 v32, v16, v29
	ds_bpermute_b32 v35, v16, v34
	s_waitcnt lgkmcnt(4)
	v_add_f32_e32 v6, v6, v7
	ds_bpermute_b32 v7, v16, v6
	s_waitcnt lgkmcnt(3)
	v_add_f32_e32 v33, v33, v36
	s_waitcnt lgkmcnt(2)
	v_add_f32_e32 v31, v29, v32
	s_waitcnt lgkmcnt(1)
	v_add_f32_e32 v29, v34, v35
	ds_bpermute_b32 v26, v17, v25
	s_waitcnt lgkmcnt(1)
	v_add_f32_e32 v6, v6, v7
	ds_bpermute_b32 v28, v17, v27
	s_waitcnt vmcnt(23)
	v_and_b32_e32 v36, 0xffff0000, v144
	v_lshlrev_b32_e32 v35, 16, v144
	s_waitcnt vmcnt(22)
	v_and_b32_e32 v38, 0xffff0000, v148
	v_mul_f32_e32 v36, v36, v36
	v_lshlrev_b32_e32 v37, 16, v148
	v_fmac_f32_e32 v36, v35, v35
	v_mul_f32_e32 v35, v38, v38
	v_and_b32_e32 v38, 0xffff0000, v145
	v_fmac_f32_e32 v35, v37, v37
	v_lshlrev_b32_e32 v37, 16, v145
	v_mul_f32_e32 v38, v38, v38
	v_and_b32_e32 v40, 0xffff0000, v149
	v_fmac_f32_e32 v38, v37, v37
	v_lshlrev_b32_e32 v39, 16, v149
	v_add_f32_e32 v38, v36, v38
	v_mul_f32_e32 v36, v40, v40
	v_fmac_f32_e32 v36, v39, v39
	v_and_b32_e32 v37, 0xffff0000, v146
	v_add_f32_e32 v35, v35, v36
	v_lshlrev_b32_e32 v36, 16, v146
	v_mul_f32_e32 v41, v37, v37
	v_fmac_f32_e32 v41, v36, v36
	v_add_co_u32_e64 v36, s[0:1], s19, v12
	v_and_b32_e32 v40, 0xffff0000, v150
	s_nop 0
	v_addc_co_u32_e64 v37, s[0:1], 0, v13, s[0:1]
	v_and_b32_e32 v37, 0xffff0000, v147
	v_lshlrev_b32_e32 v36, 16, v147
	v_mul_f32_e32 v37, v37, v37
	v_add_f32_e32 v38, v41, v38
	v_fmac_f32_e32 v37, v36, v36
	v_lshlrev_b32_e32 v39, 16, v150
	v_add_f32_e32 v36, v37, v38
	v_mul_f32_e32 v38, v40, v40
	v_fmac_f32_e32 v38, v39, v39
	v_and_b32_e32 v39, 0xffff0000, v151
	v_add_f32_e32 v35, v38, v35
	v_lshlrev_b32_e32 v38, 16, v151
	v_mul_f32_e32 v39, v39, v39
	v_fmac_f32_e32 v39, v38, v38
	v_add_f32_e32 v40, v39, v35
	s_waitcnt vmcnt(21)
	v_and_b32_e32 v39, 0xffff0000, v152
	v_lshlrev_b32_e32 v38, 16, v152
	s_waitcnt vmcnt(20)
	v_and_b32_e32 v42, 0xffff0000, v156
	v_mul_f32_e32 v39, v39, v39
	v_lshlrev_b32_e32 v41, 16, v156
	v_fmac_f32_e32 v39, v38, v38
	v_mul_f32_e32 v38, v42, v42
	v_and_b32_e32 v42, 0xffff0000, v153
	v_fmac_f32_e32 v38, v41, v41
	v_lshlrev_b32_e32 v41, 16, v153
	v_mul_f32_e32 v42, v42, v42
	v_and_b32_e32 v48, 0xffff0000, v157
	v_fmac_f32_e32 v42, v41, v41
	v_lshlrev_b32_e32 v43, 16, v157
	v_add_f32_e32 v41, v39, v42
	v_mul_f32_e32 v39, v48, v48
	v_fmac_f32_e32 v39, v43, v43
	v_add_f32_e32 v42, v38, v39
	v_and_b32_e32 v39, 0xffff0000, v154
	v_lshlrev_b32_e32 v38, 16, v154
	v_mul_f32_e32 v52, v39, v39
	v_fmac_f32_e32 v52, v38, v38
	v_add_co_u32_e64 v38, s[0:1], s20, v12
	v_add_f32_e32 v41, v52, v41
	s_nop 0
	v_addc_co_u32_e64 v39, s[0:1], 0, v13, s[0:1]
	ds_bpermute_b32 v37, v15, v36
	v_and_b32_e32 v56, 0xffff0000, v158
	v_lshlrev_b32_e32 v43, 16, v158
	v_mul_f32_e32 v38, v56, v56
	v_fmac_f32_e32 v38, v43, v43
	s_waitcnt lgkmcnt(0)
	v_add_f32_e32 v36, v36, v37
	ds_bpermute_b32 v37, v16, v36
	v_add_f32_e32 v38, v38, v42
	v_and_b32_e32 v42, 0xffff0000, v155
	v_lshlrev_b32_e32 v39, 16, v155
	v_mul_f32_e32 v42, v42, v42
	v_and_b32_e32 v56, 0xffff0000, v159
	v_fmac_f32_e32 v42, v39, v39
	v_lshlrev_b32_e32 v43, 16, v159
	v_add_f32_e32 v39, v42, v41
	v_mul_f32_e32 v41, v56, v56
	s_waitcnt lgkmcnt(0)
	v_add_f32_e32 v35, v36, v37
	ds_bpermute_b32 v37, v15, v40
	v_fmac_f32_e32 v41, v43, v43
	ds_bpermute_b32 v42, v15, v39
	v_add_f32_e32 v38, v41, v38
	ds_bpermute_b32 v41, v15, v38
	s_waitcnt lgkmcnt(2)
	v_add_f32_e32 v37, v40, v37
	ds_bpermute_b32 v40, v16, v37
	s_waitcnt lgkmcnt(2)
	v_add_f32_e32 v42, v39, v42
	ds_bpermute_b32 v43, v16, v42
	s_waitcnt lgkmcnt(2)
	v_add_f32_e32 v41, v38, v41
	ds_bpermute_b32 v56, v16, v41
	s_waitcnt lgkmcnt(2)
	v_add_f32_e32 v39, v37, v40
	ds_bpermute_b32 v3, v17, v2
	s_waitcnt lgkmcnt(2)
	v_add_f32_e32 v37, v42, v43
	ds_bpermute_b32 v1, v17, v0
	s_waitcnt lgkmcnt(2)
	v_add_f32_e32 v41, v41, v56
	ds_bpermute_b32 v5, v17, v4
	s_waitcnt vmcnt(19)
	v_lshlrev_b32_e32 v43, 16, v160
	v_and_b32_e32 v44, 0xffff0000, v160
	s_waitcnt vmcnt(18)
; DI void ph_knorm(const Params& p) {
;     ...
;         for (int i = 0; i < 18; ++i) {
;             const u32x4 va = *(const u32x4*)(base + (size_t)i * 2048 + 512), vb = *(const u32x4*)(base + (size_t)i * 2048 + 1536);
;             float sa = 0.f, sb = 0.f;
; #pragma unroll
;             for (int e = 0; e < 4; ++e) {
;                 const float a0 = __uint_as_float(va[e] << 16), a1 = __uint_as_float(va[e] & 0xffff0000u);
;                 const float b0 = __uint_as_float(vb[e] << 16), b1 = __uint_as_float(vb[e] & 0xffff0000u);
;                 sa += a0 * a0 + a1 * a1; sb += b0 * b0 + b1 * b1;
;             }
;             sa += __shfl_xor(sa, 1); sa += __shfl_xor(sa, 2); sa += __shfl_xor(sa, 4);
;             sb += __shfl_xor(sb, 1); sb += __shfl_xor(sb, 2); sb += __shfl_xor(sb, 4);
;             mxa = fmaxf(mxa, sa); mxb = fmaxf(mxb, sb);
;         }
	v_and_b32_e32 v57, 0xffff0000, v164
	v_mul_f32_e32 v44, v44, v44
	v_lshlrev_b32_e32 v56, 16, v164
	v_fmac_f32_e32 v44, v43, v43
	v_mul_f32_e32 v43, v57, v57
	v_fmac_f32_e32 v43, v56, v56
	v_lshlrev_b32_e32 v56, 16, v161
	v_and_b32_e32 v45, 0xffff0000, v161
	v_mul_f32_e32 v45, v45, v45
	v_and_b32_e32 v58, 0xffff0000, v165
	v_fmac_f32_e32 v45, v56, v56
	v_lshlrev_b32_e32 v57, 16, v165
	v_add_f32_e32 v60, v44, v45
	v_mul_f32_e32 v44, v58, v58
	v_fmac_f32_e32 v44, v57, v57
	v_and_b32_e32 v45, 0xffff0000, v162
	v_add_f32_e32 v43, v43, v44
	v_lshlrev_b32_e32 v44, 16, v162
	v_mul_f32_e32 v61, v45, v45
	v_fmac_f32_e32 v61, v44, v44
	v_add_co_u32_e64 v44, s[0:1], s21, v12
	v_lshlrev_b32_e32 v46, 16, v166
	v_and_b32_e32 v64, 0xffff0000, v166
	v_addc_co_u32_e64 v45, s[0:1], 0, v13, s[0:1]
	v_add_f32_e32 v66, v61, v60
	v_lshlrev_b32_e32 v44, 16, v163
	v_and_b32_e32 v45, 0xffff0000, v163
	v_mul_f32_e32 v47, v64, v64
	v_fmac_f32_e32 v47, v46, v46
	v_add_f32_e32 v43, v47, v43
	v_and_b32_e32 v47, 0xffff0000, v167
	v_lshlrev_b32_e32 v46, 16, v167
	v_mul_f32_e32 v47, v47, v47
	v_fmac_f32_e32 v47, v46, v46
	v_add_f32_e32 v72, v47, v43
	v_mul_f32_e32 v45, v45, v45
	v_fmac_f32_e32 v45, v44, v44
	v_add_f32_e32 v44, v45, v66
	s_waitcnt vmcnt(17)
	v_and_b32_e32 v47, 0xffff0000, v168
	v_lshlrev_b32_e32 v46, 16, v168
	s_waitcnt vmcnt(16)
	v_lshlrev_b32_e32 v48, 16, v172
	v_and_b32_e32 v52, 0xffff0000, v172
	v_mul_f32_e32 v47, v47, v47
	v_fmac_f32_e32 v47, v46, v46
	v_mul_f32_e32 v46, v52, v52
	v_fmac_f32_e32 v46, v48, v48
	v_lshlrev_b32_e32 v48, 16, v169
	v_and_b32_e32 v49, 0xffff0000, v169
	v_mul_f32_e32 v49, v49, v49
	v_lshlrev_b32_e32 v52, 16, v173
	v_and_b32_e32 v53, 0xffff0000, v173
	v_fmac_f32_e32 v49, v48, v48
	v_add_f32_e32 v48, v47, v49
	v_mul_f32_e32 v47, v53, v53
	v_fmac_f32_e32 v47, v52, v52
	v_add_f32_e32 v49, v46, v47
	v_and_b32_e32 v47, 0xffff0000, v170
	v_lshlrev_b32_e32 v46, 16, v170
	v_mul_f32_e32 v53, v47, v47
	v_fmac_f32_e32 v53, v46, v46
	v_add_co_u32_e64 v46, s[0:1], s22, v12
	ds_bpermute_b32 v45, v15, v44
	s_nop 0
	v_addc_co_u32_e64 v47, s[0:1], 0, v13, s[0:1]
	v_and_b32_e32 v52, 0xffff0000, v174
	v_lshlrev_b32_e32 v50, 16, v174
	v_mul_f32_e32 v46, v52, v52
	v_fmac_f32_e32 v46, v50, v50
	s_waitcnt lgkmcnt(0)
	v_add_f32_e32 v44, v44, v45
	v_add_f32_e32 v46, v46, v49
	v_and_b32_e32 v49, 0xffff0000, v171
	ds_bpermute_b32 v45, v16, v44
	v_lshlrev_b32_e32 v47, 16, v171
	v_mul_f32_e32 v49, v49, v49
	v_add_f32_e32 v48, v53, v48
	v_and_b32_e32 v51, 0xffff0000, v175
	v_fmac_f32_e32 v49, v47, v47
	v_lshlrev_b32_e32 v50, 16, v175
	v_add_f32_e32 v47, v49, v48
	v_mul_f32_e32 v48, v51, v51
	v_fmac_f32_e32 v48, v50, v50
	v_add_f32_e32 v46, v48, v46
	s_waitcnt lgkmcnt(0)
	v_add_f32_e32 v43, v44, v45
	ds_bpermute_b32 v45, v15, v72
	ds_bpermute_b32 v49, v15, v47
	ds_bpermute_b32 v48, v15, v46
	ds_bpermute_b32 v7, v17, v6
	ds_bpermute_b32 v32, v17, v31
	s_waitcnt lgkmcnt(4)
	v_add_f32_e32 v45, v72, v45
	s_waitcnt lgkmcnt(3)
	v_add_f32_e32 v49, v47, v49
	s_waitcnt lgkmcnt(2)
	v_add_f32_e32 v52, v46, v48
	ds_bpermute_b32 v50, v16, v45
	ds_bpermute_b32 v51, v16, v49
	ds_bpermute_b32 v53, v16, v52
	ds_bpermute_b32 v30, v17, v29
	ds_bpermute_b32 v34, v17, v33
	s_waitcnt lgkmcnt(4)
	v_add_f32_e32 v47, v45, v50
	s_waitcnt lgkmcnt(3)
	v_add_f32_e32 v45, v49, v51
	s_waitcnt lgkmcnt(2)
	v_add_f32_e32 v49, v52, v53
	s_waitcnt vmcnt(15)
	v_and_b32_e32 v52, 0xffff0000, v176
	v_lshlrev_b32_e32 v51, 16, v176
	s_waitcnt vmcnt(14)
	v_and_b32_e32 v54, 0xffff0000, v180
	v_mul_f32_e32 v52, v52, v52
	v_lshlrev_b32_e32 v53, 16, v180
	v_fmac_f32_e32 v52, v51, v51
	v_mul_f32_e32 v51, v54, v54
	v_and_b32_e32 v54, 0xffff0000, v177
	v_fmac_f32_e32 v51, v53, v53
	v_lshlrev_b32_e32 v53, 16, v177
	v_mul_f32_e32 v54, v54, v54
	v_and_b32_e32 v56, 0xffff0000, v181
	v_fmac_f32_e32 v54, v53, v53
	v_lshlrev_b32_e32 v55, 16, v181
	v_add_f32_e32 v54, v52, v54
	v_mul_f32_e32 v52, v56, v56
	v_fmac_f32_e32 v52, v55, v55
	v_and_b32_e32 v53, 0xffff0000, v178
	v_add_f32_e32 v51, v51, v52
	v_lshlrev_b32_e32 v52, 16, v178
	v_mul_f32_e32 v57, v53, v53
	v_fmac_f32_e32 v57, v52, v52
	v_add_co_u32_e64 v52, s[0:1], s23, v12
	v_and_b32_e32 v56, 0xffff0000, v182
	s_nop 0
	v_addc_co_u32_e64 v53, s[0:1], 0, v13, s[0:1]
	v_and_b32_e32 v53, 0xffff0000, v179
	v_lshlrev_b32_e32 v52, 16, v179
	v_mul_f32_e32 v53, v53, v53
	v_add_f32_e32 v54, v57, v54
	v_fmac_f32_e32 v53, v52, v52
	v_lshlrev_b32_e32 v55, 16, v182
	v_add_f32_e32 v52, v53, v54
	v_mul_f32_e32 v54, v56, v56
	v_fmac_f32_e32 v54, v55, v55
	v_and_b32_e32 v55, 0xffff0000, v183
	v_add_f32_e32 v51, v54, v51
	v_lshlrev_b32_e32 v54, 16, v183
	v_mul_f32_e32 v55, v55, v55
	v_fmac_f32_e32 v55, v54, v54
	v_add_f32_e32 v56, v55, v51
	s_waitcnt vmcnt(13)
	v_and_b32_e32 v55, 0xffff0000, v184
	v_lshlrev_b32_e32 v54, 16, v184
	s_waitcnt vmcnt(12)
	v_and_b32_e32 v58, 0xffff0000, v188
	v_mul_f32_e32 v55, v55, v55
	v_lshlrev_b32_e32 v57, 16, v188
	v_fmac_f32_e32 v55, v54, v54
	v_mul_f32_e32 v54, v58, v58
	v_and_b32_e32 v58, 0xffff0000, v185
	v_fmac_f32_e32 v54, v57, v57
	v_lshlrev_b32_e32 v57, 16, v185
	v_mul_f32_e32 v58, v58, v58
	v_and_b32_e32 v60, 0xffff0000, v189
	v_fmac_f32_e32 v58, v57, v57
	v_lshlrev_b32_e32 v59, 16, v189
	v_add_f32_e32 v57, v55, v58
	v_mul_f32_e32 v55, v60, v60
	v_fmac_f32_e32 v55, v59, v59
	v_add_f32_e32 v58, v54, v55
	v_and_b32_e32 v55, 0xffff0000, v186
	v_lshlrev_b32_e32 v54, 16, v186
	v_mul_f32_e32 v61, v55, v55
	v_fmac_f32_e32 v61, v54, v54
	v_add_co_u32_e64 v54, s[0:1], s24, v12
	ds_bpermute_b32 v53, v15, v52
	s_nop 0
	v_addc_co_u32_e64 v55, s[0:1], 0, v13, s[0:1]
	v_and_b32_e32 v60, 0xffff0000, v190
	v_lshlrev_b32_e32 v59, 16, v190
	v_mul_f32_e32 v54, v60, v60
	v_fmac_f32_e32 v54, v59, v59
	v_add_f32_e32 v54, v54, v58
	v_and_b32_e32 v58, 0xffff0000, v187
	s_waitcnt lgkmcnt(0)
; DI void ph_knorm(const Params& p) {
;     ...
;         for (int i = 0; i < 18; ++i) {
;             const u32x4 va = *(const u32x4*)(base + (size_t)i * 2048 + 512), vb = *(const u32x4*)(base + (size_t)i * 2048 + 1536);
;             float sa = 0.f, sb = 0.f;
; #pragma unroll
;             for (int e = 0; e < 4; ++e) {
;                 const float a0 = __uint_as_float(va[e] << 16), a1 = __uint_as_float(va[e] & 0xffff0000u);
;                 const float b0 = __uint_as_float(vb[e] << 16), b1 = __uint_as_float(vb[e] & 0xffff0000u);
;                 sa += a0 * a0 + a1 * a1; sb += b0 * b0 + b1 * b1;
;             }
;             sa += __shfl_xor(sa, 1); sa += __shfl_xor(sa, 2); sa += __shfl_xor(sa, 4);
;             sb += __shfl_xor(sb, 1); sb += __shfl_xor(sb, 2); sb += __shfl_xor(sb, 4);
;             mxa = fmaxf(mxa, sa); mxb = fmaxf(mxb, sb);
;         }
	v_add_f32_e32 v52, v52, v53
	v_lshlrev_b32_e32 v55, 16, v187
	v_mul_f32_e32 v58, v58, v58
	ds_bpermute_b32 v53, v16, v52
	v_add_f32_e32 v57, v61, v57
	v_and_b32_e32 v60, 0xffff0000, v191
	v_fmac_f32_e32 v58, v55, v55
	v_lshlrev_b32_e32 v59, 16, v191
	v_add_f32_e32 v55, v58, v57
	v_mul_f32_e32 v57, v60, v60
	v_fmac_f32_e32 v57, v59, v59
	v_add_f32_e32 v54, v57, v54
	ds_bpermute_b32 v57, v15, v54
	s_waitcnt lgkmcnt(1)
	v_add_f32_e32 v51, v52, v53
	ds_bpermute_b32 v53, v15, v56
	ds_bpermute_b32 v58, v15, v55
	ds_bpermute_b32 v36, v17, v35
	s_waitcnt lgkmcnt(3)
	v_add_f32_e32 v57, v54, v57
	ds_bpermute_b32 v60, v16, v57
	s_waitcnt lgkmcnt(3)
	v_add_f32_e32 v53, v56, v53
	s_waitcnt lgkmcnt(2)
	v_add_f32_e32 v58, v55, v58
	ds_bpermute_b32 v56, v16, v53
	ds_bpermute_b32 v59, v16, v58
	s_waitcnt lgkmcnt(2)
	v_add_f32_e32 v57, v57, v60
	ds_bpermute_b32 v40, v17, v39
	ds_bpermute_b32 v38, v17, v37
	s_waitcnt lgkmcnt(3)
	v_add_f32_e32 v55, v53, v56
	s_waitcnt lgkmcnt(2)
	v_add_f32_e32 v53, v58, v59
	s_waitcnt vmcnt(11)
	v_and_b32_e32 v60, 0xffff0000, v192
	v_lshlrev_b32_e32 v59, 16, v192
	s_waitcnt vmcnt(10)
	v_and_b32_e32 v66, 0xffff0000, v196
	v_mul_f32_e32 v60, v60, v60
	v_lshlrev_b32_e32 v61, 16, v196
	v_fmac_f32_e32 v60, v59, v59
	v_mul_f32_e32 v59, v66, v66
	v_and_b32_e32 v66, 0xffff0000, v193
	v_fmac_f32_e32 v59, v61, v61
	v_lshlrev_b32_e32 v61, 16, v193
	v_mul_f32_e32 v66, v66, v66
	v_and_b32_e32 v68, 0xffff0000, v197
	v_fmac_f32_e32 v66, v61, v61
	v_lshlrev_b32_e32 v67, 16, v197
	v_add_f32_e32 v66, v60, v66
	v_mul_f32_e32 v60, v68, v68
	v_fmac_f32_e32 v60, v67, v67
	v_and_b32_e32 v61, 0xffff0000, v194
	v_add_f32_e32 v59, v59, v60
	v_lshlrev_b32_e32 v60, 16, v194
	v_mul_f32_e32 v73, v61, v61
	v_fmac_f32_e32 v73, v60, v60
	v_add_co_u32_e64 v60, s[0:1], s25, v12
	v_and_b32_e32 v72, 0xffff0000, v198
	s_nop 0
	v_addc_co_u32_e64 v61, s[0:1], 0, v13, s[0:1]
	v_and_b32_e32 v61, 0xffff0000, v195
	v_lshlrev_b32_e32 v60, 16, v195
	v_mul_f32_e32 v61, v61, v61
	v_add_f32_e32 v66, v73, v66
	v_fmac_f32_e32 v61, v60, v60
	v_lshlrev_b32_e32 v67, 16, v198
	v_add_f32_e32 v60, v61, v66
	v_mul_f32_e32 v66, v72, v72
	v_fmac_f32_e32 v66, v67, v67
	v_and_b32_e32 v67, 0xffff0000, v199
	v_add_f32_e32 v59, v66, v59
	v_lshlrev_b32_e32 v66, 16, v199
	v_mul_f32_e32 v67, v67, v67
	v_fmac_f32_e32 v67, v66, v66
	v_add_f32_e32 v66, v67, v59
	s_waitcnt vmcnt(9)
	v_lshlrev_b32_e32 v67, 16, v200
	v_and_b32_e32 v62, 0xffff0000, v200
	s_waitcnt vmcnt(8)
	v_and_b32_e32 v73, 0xffff0000, v204
	v_mul_f32_e32 v62, v62, v62
	v_lshlrev_b32_e32 v72, 16, v204
	v_fmac_f32_e32 v62, v67, v67
	v_mul_f32_e32 v67, v73, v73
	v_fmac_f32_e32 v67, v72, v72
	v_lshlrev_b32_e32 v72, 16, v201
	v_and_b32_e32 v63, 0xffff0000, v201
	v_mul_f32_e32 v63, v63, v63
	v_and_b32_e32 v74, 0xffff0000, v205
	v_fmac_f32_e32 v63, v72, v72
	v_lshlrev_b32_e32 v73, 16, v205
	v_add_f32_e32 v76, v62, v63
	v_mul_f32_e32 v62, v74, v74
	v_fmac_f32_e32 v62, v73, v73
	v_and_b32_e32 v63, 0xffff0000, v202
	v_add_f32_e32 v67, v67, v62
	v_lshlrev_b32_e32 v62, 16, v202
	v_mul_f32_e32 v77, v63, v63
	v_fmac_f32_e32 v77, v62, v62
	v_add_co_u32_e64 v62, s[0:1], s26, v12
	v_add_f32_e32 v81, v77, v76
	s_nop 0
	v_addc_co_u32_e64 v63, s[0:1], 0, v13, s[0:1]
	ds_bpermute_b32 v61, v15, v60
	v_and_b32_e32 v80, 0xffff0000, v206
	v_lshlrev_b32_e32 v64, 16, v206
	v_mul_f32_e32 v62, v80, v80
	v_fmac_f32_e32 v62, v64, v64
	s_waitcnt lgkmcnt(0)
	v_add_f32_e32 v60, v60, v61
	ds_bpermute_b32 v61, v16, v60
	v_and_b32_e32 v64, 0xffff0000, v203
	v_lshlrev_b32_e32 v63, 16, v203
	v_mul_f32_e32 v64, v64, v64
	v_add_f32_e32 v62, v62, v67
	v_and_b32_e32 v67, 0xffff0000, v207
	v_fmac_f32_e32 v64, v63, v63
	v_lshlrev_b32_e32 v65, 16, v207
	v_add_f32_e32 v63, v64, v81
	v_mul_f32_e32 v64, v67, v67
	v_fmac_f32_e32 v64, v65, v65
	s_waitcnt lgkmcnt(0)
	v_add_f32_e32 v59, v60, v61
	ds_bpermute_b32 v61, v15, v66
	ds_bpermute_b32 v65, v15, v63
	v_add_f32_e32 v62, v64, v62
	ds_bpermute_b32 v64, v15, v62
	ds_bpermute_b32 v42, v17, v41
	s_waitcnt lgkmcnt(3)
	v_add_f32_e32 v61, v66, v61
	s_waitcnt lgkmcnt(2)
	v_add_f32_e32 v65, v63, v65
	ds_bpermute_b32 v66, v16, v61
	ds_bpermute_b32 v67, v16, v65
	s_waitcnt lgkmcnt(3)
	v_add_f32_e32 v80, v62, v64
	ds_bpermute_b32 v81, v16, v80
	ds_bpermute_b32 v44, v17, v43
	s_waitcnt lgkmcnt(3)
	v_add_f32_e32 v63, v61, v66
	s_waitcnt lgkmcnt(2)
	v_add_f32_e32 v61, v65, v67
	ds_bpermute_b32 v48, v17, v47
	s_waitcnt lgkmcnt(2)
	v_add_f32_e32 v65, v80, v81
	s_waitcnt vmcnt(7)
	v_lshlrev_b32_e32 v67, 16, v212
	v_and_b32_e32 v68, 0xffff0000, v212
	s_waitcnt vmcnt(6)
	v_and_b32_e32 v81, 0xffff0000, v216
	v_mul_f32_e32 v68, v68, v68
	v_lshlrev_b32_e32 v80, 16, v216
	v_fmac_f32_e32 v68, v67, v67
	v_mul_f32_e32 v67, v81, v81
	v_fmac_f32_e32 v67, v80, v80
	v_lshlrev_b32_e32 v80, 16, v213
	v_and_b32_e32 v69, 0xffff0000, v213
	v_mul_f32_e32 v69, v69, v69
	v_and_b32_e32 v82, 0xffff0000, v217
	v_fmac_f32_e32 v69, v80, v80
	v_lshlrev_b32_e32 v81, 16, v217
	v_add_f32_e32 v84, v68, v69
	v_mul_f32_e32 v68, v82, v82
	v_fmac_f32_e32 v68, v81, v81
	v_and_b32_e32 v69, 0xffff0000, v214
	v_add_f32_e32 v67, v67, v68
	v_lshlrev_b32_e32 v68, 16, v214
	v_lshlrev_b32_e32 v70, 16, v218
	v_and_b32_e32 v85, 0xffff0000, v218
	v_mul_f32_e32 v86, v69, v69
	v_fmac_f32_e32 v86, v68, v68
	v_add_co_u32_e64 v68, s[0:1], s27, v12
	v_add_f32_e32 v84, v86, v84
	s_nop 0
	v_addc_co_u32_e64 v69, s[0:1], 0, v13, s[0:1]
	v_lshlrev_b32_e32 v68, 16, v215
	v_and_b32_e32 v69, 0xffff0000, v215
	v_mul_f32_e32 v71, v85, v85
	v_fmac_f32_e32 v71, v70, v70
	v_add_f32_e32 v67, v71, v67
	v_and_b32_e32 v71, 0xffff0000, v219
	v_lshlrev_b32_e32 v70, 16, v219
	v_mul_f32_e32 v71, v71, v71
	v_mul_f32_e32 v69, v69, v69
	v_fmac_f32_e32 v71, v70, v70
	v_fmac_f32_e32 v69, v68, v68
	v_add_f32_e32 v70, v71, v67
	v_add_f32_e32 v68, v69, v84
	s_waitcnt vmcnt(5)
; DI void ph_knorm(const Params& p) {
;     ...
;         for (int i = 0; i < 18; ++i) {
;             const u32x4 va = *(const u32x4*)(base + (size_t)i * 2048 + 512), vb = *(const u32x4*)(base + (size_t)i * 2048 + 1536);
;             float sa = 0.f, sb = 0.f;
; #pragma unroll
;             for (int e = 0; e < 4; ++e) {
;                 const float a0 = __uint_as_float(va[e] << 16), a1 = __uint_as_float(va[e] & 0xffff0000u);
;                 const float b0 = __uint_as_float(vb[e] << 16), b1 = __uint_as_float(vb[e] & 0xffff0000u);
;                 sa += a0 * a0 + a1 * a1; sb += b0 * b0 + b1 * b1;
;             }
;             sa += __shfl_xor(sa, 1); sa += __shfl_xor(sa, 2); sa += __shfl_xor(sa, 4);
;             sb += __shfl_xor(sb, 1); sb += __shfl_xor(sb, 2); sb += __shfl_xor(sb, 4);
;             mxa = fmaxf(mxa, sa); mxb = fmaxf(mxb, sb);
;         }
;         if ((lane & 7) == 0) {
;             atomicMax(knm + b * 16 + (lane >> 3), __float_as_uint(mxa));
;             atomicMax(knm + b * 16 + 8 + (lane >> 3), __float_as_uint(mxb));
	v_lshlrev_b32_e32 v71, 16, v220
	v_and_b32_e32 v72, 0xffff0000, v220
	s_waitcnt vmcnt(4)
	v_lshlrev_b32_e32 v84, 16, v224
	v_and_b32_e32 v76, 0xffff0000, v224
	v_mul_f32_e32 v72, v72, v72
	v_fmac_f32_e32 v72, v71, v71
	v_mul_f32_e32 v71, v76, v76
	v_lshlrev_b32_e32 v76, 16, v221
	v_and_b32_e32 v73, 0xffff0000, v221
	v_mul_f32_e32 v73, v73, v73
	v_fmac_f32_e32 v71, v84, v84
	v_lshlrev_b32_e32 v84, 16, v225
	v_and_b32_e32 v77, 0xffff0000, v225
	v_fmac_f32_e32 v73, v76, v76
	v_add_co_u32_e64 v12, s[0:1], s28, v12
	v_add_f32_e32 v72, v72, v73
	v_mul_f32_e32 v73, v77, v77
	v_addc_co_u32_e64 v13, s[0:1], 0, v13, s[0:1]
	v_fmac_f32_e32 v73, v84, v84
	v_and_b32_e32 v12, 0xffff0000, v222
	v_add_f32_e32 v71, v71, v73
	v_lshlrev_b32_e32 v73, 16, v222
	v_mul_f32_e32 v12, v12, v12
	v_and_b32_e32 v74, 0xffff0000, v226
	v_fmac_f32_e32 v12, v73, v73
	v_lshlrev_b32_e32 v13, 16, v226
	v_add_f32_e32 v12, v12, v72
	v_mul_f32_e32 v72, v74, v74
	v_fmac_f32_e32 v72, v13, v13
	v_add_f32_e32 v13, v72, v71
	v_and_b32_e32 v72, 0xffff0000, v223
	v_lshlrev_b32_e32 v71, 16, v223
	v_and_b32_e32 v74, 0xffff0000, v227
	v_mul_f32_e32 v72, v72, v72
	v_lshlrev_b32_e32 v73, 16, v227
	v_fmac_f32_e32 v72, v71, v71
	v_mul_f32_e32 v71, v74, v74
	v_fmac_f32_e32 v71, v73, v73
	v_add_f32_e32 v13, v71, v13
	ds_bpermute_b32 v71, v15, v13
	ds_bpermute_b32 v69, v15, v68
	v_add_f32_e32 v12, v72, v12
	ds_bpermute_b32 v72, v15, v12
	ds_bpermute_b32 v46, v17, v45
	s_waitcnt lgkmcnt(3)
	v_add_f32_e32 v71, v13, v71
	ds_bpermute_b32 v73, v16, v71
	s_waitcnt lgkmcnt(3)
	v_add_f32_e32 v68, v68, v69
	ds_bpermute_b32 v69, v16, v68
	s_waitcnt lgkmcnt(3)
	v_add_f32_e32 v12, v12, v72
	ds_bpermute_b32 v72, v16, v12
	s_waitcnt lgkmcnt(2)
	v_add_f32_e32 v71, v71, v73
	ds_bpermute_b32 v50, v17, v49
	s_waitcnt lgkmcnt(2)
	v_add_f32_e32 v67, v68, v69
	ds_bpermute_b32 v69, v15, v70
	s_waitcnt lgkmcnt(2)
	v_add_f32_e32 v12, v12, v72
	ds_bpermute_b32 v52, v17, v51
	ds_bpermute_b32 v56, v17, v55
	ds_bpermute_b32 v54, v17, v53
	s_waitcnt lgkmcnt(3)
	v_add_f32_e32 v69, v70, v69
	ds_bpermute_b32 v70, v16, v69
	ds_bpermute_b32 v58, v17, v57
	s_waitcnt vmcnt(3)
	v_and_b32_e32 v74, 0xffff0000, v228
	v_lshlrev_b32_e32 v73, 16, v228
	s_waitcnt vmcnt(2)
	v_and_b32_e32 v76, 0xffff0000, v232
	v_mul_f32_e32 v74, v74, v74
	v_lshlrev_b32_e32 v75, 16, v232
	v_fmac_f32_e32 v74, v73, v73
	v_mul_f32_e32 v73, v76, v76
	v_and_b32_e32 v76, 0xffff0000, v229
	v_fmac_f32_e32 v73, v75, v75
	v_lshlrev_b32_e32 v75, 16, v229
	v_and_b32_e32 v78, 0xffff0000, v233
	v_mul_f32_e32 v76, v76, v76
	v_lshlrev_b32_e32 v77, 16, v233
	v_fmac_f32_e32 v76, v75, v75
	v_mul_f32_e32 v75, v78, v78
	v_add_f32_e32 v74, v74, v76
	v_fmac_f32_e32 v75, v77, v77
	v_and_b32_e32 v76, 0xffff0000, v230
	v_add_f32_e32 v73, v73, v75
	v_lshlrev_b32_e32 v75, 16, v230
	v_mul_f32_e32 v76, v76, v76
	v_fmac_f32_e32 v76, v75, v75
	v_add_f32_e32 v74, v76, v74
	v_and_b32_e32 v76, 0xffff0000, v231
	v_lshlrev_b32_e32 v75, 16, v231
	v_mul_f32_e32 v76, v76, v76
	v_and_b32_e32 v78, 0xffff0000, v234
	v_fmac_f32_e32 v76, v75, v75
	v_lshlrev_b32_e32 v77, 16, v234
	v_add_f32_e32 v74, v76, v74
	v_mul_f32_e32 v76, v78, v78
	v_fmac_f32_e32 v76, v77, v77
	v_and_b32_e32 v77, 0xffff0000, v235
	v_add_f32_e32 v73, v76, v73
	v_lshlrev_b32_e32 v76, 16, v235
	v_mul_f32_e32 v77, v77, v77
	v_fmac_f32_e32 v77, v76, v76
	s_waitcnt vmcnt(1)
	v_and_b32_e32 v78, 0xffff0000, v236
	v_add_f32_e32 v76, v77, v73
	v_lshlrev_b32_e32 v77, 16, v236
	s_waitcnt vmcnt(0)
	v_and_b32_e32 v80, 0xffff0000, v240
	v_mul_f32_e32 v78, v78, v78
	ds_bpermute_b32 v75, v15, v74
	v_lshlrev_b32_e32 v79, 16, v240
	v_fmac_f32_e32 v78, v77, v77
	v_mul_f32_e32 v77, v80, v80
	v_and_b32_e32 v80, 0xffff0000, v237
	v_fmac_f32_e32 v77, v79, v79
	v_lshlrev_b32_e32 v79, 16, v237
	v_and_b32_e32 v82, 0xffff0000, v241
	v_mul_f32_e32 v80, v80, v80
	v_lshlrev_b32_e32 v81, 16, v241
	v_fmac_f32_e32 v80, v79, v79
	v_mul_f32_e32 v79, v82, v82
	v_add_f32_e32 v78, v78, v80
	v_fmac_f32_e32 v79, v81, v81
	v_and_b32_e32 v80, 0xffff0000, v238
	v_add_f32_e32 v77, v77, v79
	v_lshlrev_b32_e32 v79, 16, v238
	v_and_b32_e32 v82, 0xffff0000, v242
	v_mul_f32_e32 v80, v80, v80
	s_waitcnt lgkmcnt(0)
	v_add_f32_e32 v74, v74, v75
	v_lshlrev_b32_e32 v81, 16, v242
	v_fmac_f32_e32 v80, v79, v79
	v_mul_f32_e32 v79, v82, v82
	ds_bpermute_b32 v75, v16, v74
	v_add_f32_e32 v78, v80, v78
	v_fmac_f32_e32 v79, v81, v81
	v_and_b32_e32 v80, 0xffff0000, v239
	v_add_f32_e32 v77, v79, v77
	v_lshlrev_b32_e32 v79, 16, v239
	v_and_b32_e32 v82, 0xffff0000, v243
	v_mul_f32_e32 v80, v80, v80
	v_lshlrev_b32_e32 v81, 16, v243
	v_fmac_f32_e32 v80, v79, v79
	v_mul_f32_e32 v79, v82, v82
	v_fmac_f32_e32 v79, v81, v81
	v_add_f32_e32 v78, v80, v78
	v_add_f32_e32 v77, v79, v77
	s_waitcnt lgkmcnt(0)
	v_add_f32_e32 v73, v74, v75
	ds_bpermute_b32 v75, v15, v76
	ds_bpermute_b32 v80, v15, v78
	ds_bpermute_b32 v79, v15, v77
	v_add_f32_e32 v69, v69, v70
	ds_bpermute_b32 v60, v17, v59
	s_waitcnt lgkmcnt(3)
	v_add_f32_e32 v75, v76, v75
	s_waitcnt lgkmcnt(2)
	v_add_f32_e32 v80, v78, v80
	s_waitcnt lgkmcnt(1)
	v_add_f32_e32 v79, v77, v79
	ds_bpermute_b32 v76, v16, v75
	ds_bpermute_b32 v81, v16, v80
	ds_bpermute_b32 v82, v16, v79
	ds_bpermute_b32 v64, v17, v63
	ds_bpermute_b32 v62, v17, v61
	s_waitcnt lgkmcnt(4)
	v_add_f32_e32 v77, v75, v76
	s_waitcnt lgkmcnt(3)
	v_add_f32_e32 v75, v80, v81
	s_waitcnt lgkmcnt(2)
	v_add_f32_e32 v79, v79, v82
	ds_bpermute_b32 v66, v17, v65
	ds_bpermute_b32 v68, v17, v67
	ds_bpermute_b32 v70, v17, v69
	ds_bpermute_b32 v13, v17, v12
	ds_bpermute_b32 v72, v17, v71
	ds_bpermute_b32 v74, v17, v73
	ds_bpermute_b32 v78, v17, v77
	ds_bpermute_b32 v76, v17, v75
	ds_bpermute_b32 v80, v17, v79
	s_and_saveexec_b64 s[0:1], vcc
	s_cbranch_execz .LBB0_537
; DI void ph_knorm(const Params& p) {
;     ...
;             sa += __shfl_xor(sa, 1); sa += __shfl_xor(sa, 2); sa += __shfl_xor(sa, 4);
;             sb += __shfl_xor(sb, 1); sb += __shfl_xor(sb, 2); sb += __shfl_xor(sb, 4);
;             mxa = fmaxf(mxa, sa); mxb = fmaxf(mxb, sb);
;         }
;         if ((lane & 7) == 0) {
;             atomicMax(knm + b * 16 + (lane >> 3), __float_as_uint(mxa));
;             atomicMax(knm + b * 16 + 8 + (lane >> 3), __float_as_uint(mxb));
;         }
	v_add_f32_e32 v23, v23, v24
	v_add_f32_e32 v24, v25, v26
	v_max3_f32 v23, v23, 0, v24
	v_add_f32_e32 v2, v2, v3
	v_add_f32_e32 v3, v4, v5
	v_max3_f32 v2, v23, v2, v3
	v_add_f32_e32 v3, v31, v32
	v_add_f32_e32 v4, v33, v34
	v_max3_f32 v2, v2, v3, v4
	v_add_f32_e32 v3, v39, v40
	v_add_f32_e32 v4, v41, v42
	v_max3_f32 v2, v2, v3, v4
	v_add_f32_e32 v3, v47, v48
	v_add_f32_e32 v4, v49, v50
	v_max3_f32 v2, v2, v3, v4
	v_add_f32_e32 v3, v55, v56
	v_add_f32_e32 v4, v57, v58
	v_max3_f32 v2, v2, v3, v4
	s_waitcnt lgkmcnt(10)
	v_add_f32_e32 v3, v63, v64
	s_waitcnt lgkmcnt(8)
	v_add_f32_e32 v4, v65, v66
	v_max3_f32 v2, v2, v3, v4
	s_waitcnt lgkmcnt(6)
	v_add_f32_e32 v3, v69, v70
	s_waitcnt lgkmcnt(4)
	v_add_f32_e32 v4, v71, v72
	v_max3_f32 v2, v2, v3, v4
	s_waitcnt lgkmcnt(2)
	v_add_f32_e32 v3, v77, v78
	s_waitcnt lgkmcnt(0)
	v_add_f32_e32 v4, v79, v80
	v_max3_f32 v2, v2, v3, v4
	v_add_f32_e32 v3, v19, v20
	v_add_f32_e32 v4, v21, v22
	v_max3_f32 v3, v3, 0, v4
	v_add_f32_e32 v4, v27, v28
	v_add_f32_e32 v0, v0, v1
	v_max3_f32 v0, v3, v4, v0
	v_add_f32_e32 v1, v6, v7
	v_add_f32_e32 v3, v29, v30
	v_max3_f32 v0, v0, v1, v3
	v_add_f32_e32 v1, v35, v36
	v_add_f32_e32 v3, v37, v38
	v_max3_f32 v0, v0, v1, v3
	v_add_f32_e32 v1, v43, v44
	v_add_f32_e32 v3, v45, v46
	v_max3_f32 v0, v0, v1, v3
	v_add_f32_e32 v1, v51, v52
	v_add_f32_e32 v3, v53, v54
	v_max3_f32 v0, v0, v1, v3
	v_add_f32_e32 v1, v59, v60
	v_add_f32_e32 v3, v61, v62
	v_max3_f32 v0, v0, v1, v3
	v_add_f32_e32 v1, v67, v68
	v_add_f32_e32 v3, v12, v13
	v_max3_f32 v0, v0, v1, v3
	v_add_f32_e32 v1, v73, v74
	v_add_f32_e32 v3, v75, v76
	v_max3_f32 v3, v0, v1, v3
	v_lshlrev_b32_e32 v0, 4, v18
	v_ashrrev_i32_e32 v1, 31, v0
	v_lshl_add_u64 v[0:1], v[0:1], 2, v[10:11]
	global_atomic_umax v[0:1], v3, off
	global_atomic_umax v[0:1], v2, off offset:32
	s_branch .LBB0_537
